# v50 with only wave 0 of each FFN-out workgroup polling the two producer flags before the FFN-out prologue (8x fewer poll loads on the flag lines)
# speedup vs baseline: 1.0066x; 1.0066x over previous
.Lko_fast_g1:
	s_cmp_lt_u32 s2, 0xa0
	s_cbranch_scc0 .Lko_g1_skip
	v_readfirstlane_b32 s22, v226
	s_cmp_gt_u32 s22, 63
	s_cbranch_scc1 .Lko_g1_skip
	v_readlane_b32 s22, v253, 45
	s_load_dwordx2 s[12:13], s[0:1], 0xe0
	s_mul_i32 s24, s22, 0xcccd
	s_lshr_b32 s24, s24, 18
	s_mul_i32 s25, s24, 5
	s_sub_i32 s25, s22, s25
	s_lshl_b32 s26, s25, 3
	s_or_b32 s26, s26, s24
	s_add_i32 s25, s25, 5
	s_lshl_b32 s27, s25, 3
	s_or_b32 s27, s27, s24
	s_lshl_b32 s22, s101, 8
	s_add_i32 s26, s26, s22
	s_add_i32 s27, s27, s22
	s_lshl_b32 s26, s26, 2
	s_lshl_b32 s27, s27, 2
	s_add_i32 s26, s26, 0xb000
	s_add_i32 s27, s27, 0xb000
	v_mov_b32_e32 v2, s26
	v_mov_b32_e32 v3, s27
	s_mov_b32 s22, 0
	s_waitcnt lgkmcnt(0)
